# k20 + attn_depk: attention score scaling de-packed (two v_mov + 2-pass v_pk_mul -> two v_mul reading the original registers, bit-identical), SGPR-mask wait states kept
# baseline (speedup 1.0000x reference)
; __device__ void phase_attn(const Params& p, unsigned char* smem, int wave) {
;     ...
;         const bf16x8 qf0 = *(const bf16x8*)(Qs + (16 * w4 + ql) * ATT_LD + gq * 8), qf1 = *(const bf16x8*)(Qs + (16 * w4 + ql) * ATT_LD + 32 + gq * 8);
;         f32x4 sc[10];
; #pragma unroll
;         for (int kt = 0; kt < 9; ++kt) { const bf16_t* kr = Ks + (16 * w4 + 16 * kt + ql) * ATT_LD + gq * 8;
;             f32x4 a = (f32x4){0.f, 0.f, 0.f, 0.f};
;             a = __builtin_amdgcn_mfma_f32_16x16x32_bf16(*(const bf16x8*)kr, qf0, a, 0, 0, 0);
;             a = __builtin_amdgcn_mfma_f32_16x16x32_bf16(*(const bf16x8*)(kr + 32), qf1, a, 0, 0, 0);
;             sc[kt] = a; if (kt % 3 == 2) __builtin_amdgcn_sched_barrier(0); }
;         const float slope = exp2f(-(float)(h + 1)) * (float)d * 1.4426950408889634f;
;         const int qi = i0 + 16 * w4 + ql;
;         float mx = -1e30f;
; #pragma unroll
;         for (int kt = 0; kt < 9; ++kt)
; #pragma unroll
;             for (int j = 0; j < 4; ++j) { const int rel = 16 * kt + 4 * gq + j - 64 - ql; const int jk = qi + rel;
;                 const bool relok = (kt == 0) ? (rel >= -64) : ((kt == 8) ? (rel <= 64) : true);
;                 const bool ok = relok && ((unsigned)jk < (unsigned)Ls);
;                 const float v = ok ? sc[kt][j] * 0.18033688011112042f - slope * fabsf((float)rel) : -1e30f;
;                 sc[kt][j] = v; mx = fmaxf(mx, v); }
.LBB0_732:
	ds_read_b128 v[46:49], v140 offset:18432
	ds_read_b128 v[186:189], v140
	ds_read_b128 v[50:53], v140 offset:18496
	ds_read_b128 v[190:193], v140 offset:64
	ds_read_b128 v[54:57], v140 offset:20736
	ds_read_b128 v[58:61], v140 offset:20800
	v_readlane_b32 s28, v253, 8
	v_readlane_b32 s30, v253, 10
	v_readlane_b32 s31, v253, 11
	s_add_u32 s59, s30, s20
	s_mul_i32 s18, s22, 0xfffffd80
	s_waitcnt lgkmcnt(4)
	v_mfma_f32_16x16x32_bf16 v[46:49], v[46:49], v[186:189], 0
	s_mul_i32 s19, s22, 0xfffec000
	s_addc_u32 s60, s31, s21
	s_add_i32 s18, s23, s18
	s_waitcnt lgkmcnt(2)
	v_mfma_f32_16x16x32_bf16 v[194:197], v[50:53], v[190:193], v[46:49]
	s_add_i32 s19, s48, s19
	s_and_b32 s57, s22, 7
	s_and_b32 s19, s19, 0xfffff800
	ds_read_b128 v[46:49], v140 offset:23040
	s_waitcnt lgkmcnt(2)
	v_mfma_f32_16x16x32_bf16 v[50:53], v[54:57], v[186:189], 0
	ds_read_b128 v[54:57], v140 offset:23104
	s_and_b32 s20, s18, 15
	s_add_i32 s21, s18, 0xfffffe00
	s_cmpk_lt_i32 s18, 0x200
	s_cselect_b32 s18, s20, s21
	s_cselect_b32 s20, s50, 0x4000
	s_cselect_b32 s61, s19, 0x10000
	s_cmp_eq_u32 s42, 1
	s_cselect_b32 s19, 4, 16
	s_cselect_b32 s21, 2, 4
	s_cmp_lt_u32 s22, 8
	s_waitcnt lgkmcnt(1)
	v_mfma_f32_16x16x32_bf16 v[46:49], v[46:49], v[186:189], 0
	s_cselect_b32 s22, 1, s19
	s_cselect_b32 s58, 0, s21
	s_add_i32 s19, s22, -1
	s_lshr_b32 s63, s20, s58
	s_and_b32 s62, s19, s18
	s_lshr_b32 s20, s18, s58
	v_readlane_b32 s29, v253, 9
	v_mfma_f32_16x16x32_bf16 v[198:201], v[58:61], v[190:193], v[50:53]
	s_waitcnt lgkmcnt(0)
	v_mfma_f32_16x16x32_bf16 v[202:205], v[54:57], v[190:193], v[46:49]
	s_nop 2
	ds_read_b128 v[46:49], v140 offset:25344
	ds_read_b128 v[50:53], v140 offset:25408
	ds_read_b128 v[54:57], v140 offset:27648
	ds_read_b128 v[58:61], v140 offset:27712
	s_waitcnt lgkmcnt(3)
	v_mfma_f32_16x16x32_bf16 v[46:49], v[46:49], v[186:189], 0
	s_waitcnt lgkmcnt(2)
	v_mfma_f32_16x16x32_bf16 v[206:209], v[50:53], v[190:193], v[46:49]
	ds_read_b128 v[50:53], v140 offset:30016
	s_nop 4
	ds_read_b128 v[46:49], v140 offset:29952
	s_waitcnt lgkmcnt(3)
	v_mfma_f32_16x16x32_bf16 v[54:57], v[54:57], v[186:189], 0
	s_waitcnt lgkmcnt(0)
	v_mfma_f32_16x16x32_bf16 v[46:49], v[46:49], v[186:189], 0
	v_mfma_f32_16x16x32_bf16 v[62:65], v[58:61], v[190:193], v[54:57]
	v_mfma_f32_16x16x32_bf16 v[58:61], v[50:53], v[190:193], v[46:49]
	s_nop 5
	ds_read_b128 v[46:49], v140 offset:32256
	ds_read_b128 v[50:53], v140 offset:32320
	ds_read_b128 v[54:57], v140 offset:34560
	ds_read_b128 v[210:213], v140 offset:34624
	s_waitcnt lgkmcnt(3)
	v_mfma_f32_16x16x32_bf16 v[46:49], v[46:49], v[186:189], 0
	s_waitcnt lgkmcnt(1)
	v_mfma_f32_16x16x32_bf16 v[214:217], v[54:57], v[186:189], 0
	v_mfma_f32_16x16x32_bf16 v[54:57], v[50:53], v[190:193], v[46:49]
	s_nop 4
	ds_read_b128 v[46:49], v140 offset:36864
	s_waitcnt lgkmcnt(1)
	v_mfma_f32_16x16x32_bf16 v[50:53], v[210:213], v[190:193], v[214:217]
	ds_read_b128 v[210:213], v140 offset:36928
	s_waitcnt lgkmcnt(1)
	v_mfma_f32_16x16x32_bf16 v[46:49], v[46:49], v[186:189], 0
	s_waitcnt lgkmcnt(0)
	v_mfma_f32_16x16x32_bf16 v[46:49], v[210:213], v[190:193], v[46:49]
	s_add_i32 s18, s57, 1
	v_cvt_f32_ubyte0_e32 v12, s18
	v_cmp_lt_f32_e32 vcc, s51, v12
	s_and_b64 s[18:19], vcc, exec
	s_cselect_b32 s18, 0xffffffc0, 0
	v_cndmask_b32_e32 v13, 0, v181, vcc
	v_sub_f32_e32 v12, v13, v12
	v_exp_f32_e32 v12, v12
	v_lshl_add_u32 v139, s20, 7, v67
	v_cvt_f32_ubyte0_e32 v13, s22
	v_or_b32_e32 v45, v139, v66
	v_ldexp_f32 v12, v12, s18
	v_mul_f32_e32 v13, v12, v13
	v_add_u32_e32 v12, v45, v143
	v_cmp_gt_u32_e64 s[26:27], s63, v12
	v_add_u32_e32 v12, v45, v144
	v_cmp_gt_u32_e64 s[28:29], s63, v12
	v_add_u32_e32 v12, v45, v145
	v_cmp_gt_u32_e64 s[30:31], s63, v12
	v_add_u32_e32 v12, v45, v146
	v_cmp_gt_u32_e64 s[34:35], s63, v12
	v_add_u32_e32 v12, v45, v174
	v_cmp_gt_u32_e64 s[22:23], s63, v12
	v_add_u32_e32 v12, v45, v175
	v_cmp_gt_u32_e64 s[20:21], s63, v12
	v_add_u32_e32 v12, v45, v176
	v_cmp_gt_u32_e32 vcc, s63, v12
	v_add_u32_e32 v12, v45, v177
	v_cmp_gt_u32_e64 s[18:19], s63, v12
	v_mov_b32_e32 v12, v49
	v_pk_mul_f32 v[12:13], v[12:13], s[44:45]
	v_mul_f32_e32 v186, v68, v194
	v_mul_f32_e32 v187, v69, v13
	s_and_b64 s[26:27], s[24:25], s[26:27]
	v_sub_f32_e32 v49, v186, v187
	v_mul_f32_e32 v186, v70, v195
	v_mul_f32_e32 v187, v71, v13
	v_cndmask_b32_e64 v194, v182, v49, s[26:27]
	v_sub_f32_e32 v49, v186, v187
	s_and_b64 s[26:27], s[4:5], s[28:29]
	v_mul_f32_e32 v186, v72, v196
	v_mul_f32_e32 v187, v73, v13
	v_cndmask_b32_e64 v195, v182, v49, s[26:27]
	v_sub_f32_e32 v186, v186, v187
	s_and_b64 s[26:27], s[6:7], s[30:31]
	v_cndmask_b32_e64 v196, v182, v186, s[26:27]
	v_mul_f32_e32 v186, v74, v197
	v_mul_f32_e32 v187, v75, v13
	s_and_b64 s[26:27], s[8:9], s[34:35]
	v_sub_f32_e32 v186, v186, v187
	v_cndmask_b32_e64 v197, v182, v186, s[26:27]
	v_add_u32_e32 v14, v45, v147
	v_mul_f32_e32 v186, v76, v198
	v_mul_f32_e32 v187, v77, v13
	v_cmp_gt_u32_e64 s[26:27], s63, v14
	v_sub_f32_e32 v186, v186, v187
	s_nop 0
	v_cndmask_b32_e64 v14, v182, v186, s[26:27]
	v_add_u32_e32 v188, v45, v148
	v_mul_f32_e32 v186, v78, v199
	v_mul_f32_e32 v187, v79, v13
	v_cmp_gt_u32_e64 s[26:27], s63, v188
	v_sub_f32_e32 v186, v186, v187
	s_nop 0
	v_cndmask_b32_e64 v188, v182, v186, s[26:27]
	v_add_u32_e32 v189, v45, v149
	v_mul_f32_e32 v186, v80, v200
	v_mul_f32_e32 v187, v81, v13
	v_cmp_gt_u32_e64 s[26:27], s63, v189
	v_sub_f32_e32 v186, v186, v187
	s_nop 0
	v_cndmask_b32_e64 v189, v182, v186, s[26:27]
	v_add_u32_e32 v190, v45, v150
	v_mul_f32_e32 v186, v82, v201
	v_mul_f32_e32 v187, v83, v13
	v_cmp_gt_u32_e64 s[26:27], s63, v190
	v_sub_f32_e32 v186, v186, v187
	s_nop 0
; __device__ void phase_attn(const Params& p, unsigned char* smem, int wave) {
;     ...
;         for (int kt = 0; kt < 9; ++kt)
; #pragma unroll
;             for (int j = 0; j < 4; ++j) { const int rel = 16 * kt + 4 * gq + j - 64 - ql; const int jk = qi + rel;
;                 const bool relok = (kt == 0) ? (rel >= -64) : ((kt == 8) ? (rel <= 64) : true);
;                 const bool ok = relok && ((unsigned)jk < (unsigned)Ls);
;                 const float v = ok ? sc[kt][j] * 0.18033688011112042f - slope * fabsf((float)rel) : -1e30f;
;                 sc[kt][j] = v; mx = fmaxf(mx, v); }
;         mx = fmaxf(mx, __shfl_xor(mx, 16)); mx = fmaxf(mx, __shfl_xor(mx, 32));
	v_cndmask_b32_e64 v190, v182, v186, s[26:27]
	v_add_u32_e32 v191, v45, v151
	v_mul_f32_e32 v186, v84, v202
	v_mul_f32_e32 v187, v85, v13
	v_cmp_gt_u32_e64 s[26:27], s63, v191
	v_sub_f32_e32 v186, v186, v187
	s_nop 0
	v_cndmask_b32_e64 v191, v182, v186, s[26:27]
	v_add_u32_e32 v192, v45, v152
	v_mul_f32_e32 v186, v86, v203
	v_mul_f32_e32 v187, v87, v13
	v_cmp_gt_u32_e64 s[26:27], s63, v192
	v_sub_f32_e32 v186, v186, v187
	s_nop 0
	v_cndmask_b32_e64 v192, v182, v186, s[26:27]
	v_add_u32_e32 v193, v45, v153
	v_mul_f32_e32 v186, v88, v204
	v_mul_f32_e32 v187, v89, v13
	v_cmp_gt_u32_e64 s[26:27], s63, v193
	v_sub_f32_e32 v186, v186, v187
	s_nop 0
	v_cndmask_b32_e64 v193, v182, v186, s[26:27]
	v_add_u32_e32 v210, v45, v154
	v_mul_f32_e32 v186, v90, v205
	v_mul_f32_e32 v187, v91, v13
	v_cmp_gt_u32_e64 s[26:27], s63, v210
	v_sub_f32_e32 v186, v186, v187
	s_nop 0
	v_cndmask_b32_e64 v198, v182, v186, s[26:27]
	v_add_u32_e32 v211, v45, v155
	v_mul_f32_e32 v186, v92, v206
	v_mul_f32_e32 v187, v93, v13
	v_cmp_gt_u32_e64 s[26:27], s63, v211
	v_sub_f32_e32 v186, v186, v187
	s_nop 0
	v_cndmask_b32_e64 v199, v182, v186, s[26:27]
	v_add_u32_e32 v212, v45, v156
	v_mul_f32_e32 v186, v94, v207
	v_mul_f32_e32 v187, v95, v13
	v_cmp_gt_u32_e64 s[26:27], s63, v212
	v_sub_f32_e32 v186, v186, v187
	s_nop 0
	v_cndmask_b32_e64 v200, v182, v186, s[26:27]
	v_add_u32_e32 v213, v45, v157
	v_mul_f32_e32 v186, v96, v208
	v_mul_f32_e32 v187, v97, v13
	v_cmp_gt_u32_e64 s[26:27], s63, v213
	v_sub_f32_e32 v186, v186, v187
	s_nop 0
	v_cndmask_b32_e64 v201, v182, v186, s[26:27]
	v_add_u32_e32 v214, v45, v158
	v_mul_f32_e32 v186, v98, v209
	v_mul_f32_e32 v187, v99, v13
	v_cmp_gt_u32_e64 s[26:27], s63, v214
	v_sub_f32_e32 v186, v186, v187
	s_nop 0
	v_cndmask_b32_e64 v202, v182, v186, s[26:27]
	v_add_u32_e32 v215, v45, v142
	v_mul_f32_e32 v186, v100, v62
	v_mul_f32_e32 v187, v101, v13
	v_cmp_gt_u32_e64 s[26:27], s63, v215
	v_sub_f32_e32 v62, v186, v187
	v_add_u32_e32 v216, v45, v159
	v_cndmask_b32_e64 v186, v182, v62, s[26:27]
	v_mul_f32_e32 v62, v102, v63
	v_mul_f32_e32 v63, v103, v13
	v_cmp_gt_u32_e64 s[26:27], s63, v216
	v_sub_f32_e32 v62, v62, v63
	s_nop 0
	v_cndmask_b32_e64 v187, v182, v62, s[26:27]
	v_add_u32_e32 v217, v45, v160
	v_mul_f32_e32 v62, v104, v64
	v_mul_f32_e32 v63, v105, v13
	v_cmp_gt_u32_e64 s[26:27], s63, v217
	v_sub_f32_e32 v62, v62, v63
	s_nop 0
	v_cndmask_b32_e64 v64, v182, v62, s[26:27]
	v_add_u32_e32 v218, v45, v161
	v_mul_f32_e32 v62, v106, v65
	v_mul_f32_e32 v63, v107, v13
	v_cmp_gt_u32_e64 s[26:27], s63, v218
	v_sub_f32_e32 v62, v62, v63
	s_nop 0
	v_cndmask_b32_e64 v65, v182, v62, s[26:27]
	v_add_u32_e32 v219, v45, v162
	v_mul_f32_e32 v62, v108, v58
	v_mul_f32_e32 v63, v109, v13
	v_cmp_gt_u32_e64 s[26:27], s63, v219
	v_sub_f32_e32 v58, v62, v63
	v_add_u32_e32 v220, v45, v163
	v_cndmask_b32_e64 v62, v182, v58, s[26:27]
	v_mul_f32_e32 v58, v110, v59
	v_mul_f32_e32 v59, v111, v13
	v_cmp_gt_u32_e64 s[26:27], s63, v220
	v_sub_f32_e32 v58, v58, v59
	s_nop 0
	v_cndmask_b32_e64 v63, v182, v58, s[26:27]
	v_add_u32_e32 v221, v45, v164
	v_mul_f32_e32 v58, v112, v60
	v_mul_f32_e32 v59, v113, v13
	v_cmp_gt_u32_e64 s[26:27], s63, v221
	v_sub_f32_e32 v58, v58, v59
	s_nop 0
	v_cndmask_b32_e64 v60, v182, v58, s[26:27]
	v_add_u32_e32 v222, v45, v165
	v_mul_f32_e32 v58, v114, v61
	v_mul_f32_e32 v59, v115, v13
	v_cmp_gt_u32_e64 s[26:27], s63, v222
	v_sub_f32_e32 v58, v58, v59
	s_nop 0
	v_cndmask_b32_e64 v61, v182, v58, s[26:27]
	v_add_u32_e32 v223, v45, v166
	v_mul_f32_e32 v58, v116, v54
	v_mul_f32_e32 v59, v117, v13
	v_cmp_gt_u32_e64 s[26:27], s63, v223
	v_sub_f32_e32 v54, v58, v59
	v_add_u32_e32 v224, v45, v167
	v_cndmask_b32_e64 v58, v182, v54, s[26:27]
	v_mul_f32_e32 v54, v118, v55
	v_mul_f32_e32 v55, v119, v13
	v_cmp_gt_u32_e64 s[26:27], s63, v224
	v_sub_f32_e32 v54, v54, v55
	s_nop 0
	v_cndmask_b32_e64 v59, v182, v54, s[26:27]
	v_add_u32_e32 v225, v45, v168
	v_mul_f32_e32 v54, v120, v56
	v_mul_f32_e32 v55, v121, v13
	v_cmp_gt_u32_e64 s[26:27], s63, v225
	v_sub_f32_e32 v54, v54, v55
	s_nop 0
	v_cndmask_b32_e64 v56, v182, v54, s[26:27]
	v_add_u32_e32 v226, v45, v169
	v_mul_f32_e32 v54, v122, v57
	v_mul_f32_e32 v55, v123, v13
	v_cmp_gt_u32_e64 s[26:27], s63, v226
	v_sub_f32_e32 v54, v54, v55
	s_nop 0
	v_cndmask_b32_e64 v57, v182, v54, s[26:27]
	v_add_u32_e32 v227, v45, v170
	v_mul_f32_e32 v54, v124, v50
	v_mul_f32_e32 v55, v125, v13
	v_cmp_gt_u32_e64 s[26:27], s63, v227
	v_sub_f32_e32 v50, v54, v55
	v_max3_f32 v49, v194, s52, v195
	v_cndmask_b32_e64 v54, v182, v50, s[26:27]
	v_add_u32_e32 v228, v45, v171
	v_max3_f32 v49, v49, v196, v197
	v_mul_f32_e32 v50, v126, v51
	v_mul_f32_e32 v51, v127, v13
	v_max3_f32 v49, v49, v14, v188
	v_sub_f32_e32 v50, v50, v51
	v_cmp_gt_u32_e64 s[26:27], s63, v228
	v_max3_f32 v49, v49, v189, v190
	s_nop 0
	v_cndmask_b32_e64 v55, v182, v50, s[26:27]
	v_add_u32_e32 v229, v45, v172
	v_max3_f32 v49, v49, v191, v192
	v_mul_f32_e32 v50, v128, v52
	v_mul_f32_e32 v51, v129, v13
	v_max3_f32 v49, v49, v193, v198
	v_sub_f32_e32 v50, v50, v51
	v_cmp_gt_u32_e64 s[26:27], s63, v229
	v_max3_f32 v49, v49, v199, v200
	s_nop 0
	v_cndmask_b32_e64 v52, v182, v50, s[26:27]
	v_add_u32_e32 v230, v45, v173
	v_max3_f32 v49, v49, v201, v202
	v_mul_f32_e32 v50, v130, v53
	v_mul_f32_e32 v51, v131, v13
	v_max3_f32 v49, v49, v186, v187
	v_sub_f32_e32 v50, v50, v51
	v_cmp_gt_u32_e64 s[26:27], s63, v230
	v_max3_f32 v49, v49, v64, v65
	s_nop 0
	v_cndmask_b32_e64 v53, v182, v50, s[26:27]
	v_max3_f32 v49, v49, v62, v63
	v_mul_f32_e32 v50, v132, v46
	v_mul_f32_e32 v51, v133, v13
	v_max3_f32 v49, v49, v60, v61
	v_sub_f32_e32 v46, v50, v51
	s_and_b64 s[22:23], s[10:11], s[22:23]
	v_max3_f32 v49, v49, v58, v59
	v_cndmask_b32_e64 v50, v182, v46, s[22:23]
	v_max3_f32 v49, v49, v56, v57
	v_mul_f32_e32 v46, v134, v47
	v_mul_f32_e32 v47, v135, v13
	v_max3_f32 v49, v49, v54, v55
	v_sub_f32_e32 v46, v46, v47
	s_and_b64 s[20:21], s[12:13], s[20:21]
	v_max3_f32 v49, v49, v52, v53
	v_cndmask_b32_e64 v51, v182, v46, s[20:21]
	v_max3_f32 v203, v49, v50, v51
	v_mov_b32_e32 v49, v13
	v_pk_mul_f32 v[46:47], v[48:49], v[136:137]
	s_and_b64 vcc, s[14:15], vcc
	v_sub_f32_e32 v46, v46, v47
	v_and_b32_e32 v206, 64, v183
	v_cndmask_b32_e32 v47, v182, v46, vcc
	v_fma_f32 v12, -v13, v178, v12
	s_and_b64 vcc, s[16:17], s[18:19]
	v_xor_b32_e32 v46, 16, v183
	v_add_u32_e32 v48, 64, v206
	v_cndmask_b32_e32 v12, v182, v12, vcc
	v_cmp_lt_i32_e32 vcc, v46, v48
	v_max3_f32 v13, v203, v47, v12
	s_nop 0
	v_cndmask_b32_e32 v46, v183, v46, vcc
	v_lshlrev_b32_e32 v203, 2, v46
	ds_bpermute_b32 v46, v203, v13
	s_waitcnt lgkmcnt(0)
; __device__ __forceinline__ unsigned cvtpk(float lo, float hi) { const f32v2_t v = {lo, hi}; const bf16v2_t b = __builtin_convertvector(v, bf16v2_t); return __builtin_bit_cast(unsigned, b); }
; __device__ __forceinline__ v4i16_t lds_tr16(const bf16_t* p) { return __builtin_amdgcn_ds_read_tr16_b64_v4i16((LAS v4i16_t*)p); }
; __device__ void phase_attn(const Params& p, unsigned char* smem, int wave) {
;     ...
;         mx = fmaxf(mx, __shfl_xor(mx, 16)); mx = fmaxf(mx, __shfl_xor(mx, 32));
;         float den = 0.f;
; #pragma unroll
;         for (int kt = 0; kt < 9; ++kt)
; #pragma unroll
;             for (int j = 0; j < 4; ++j) { const float pv = __builtin_amdgcn_exp2f(sc[kt][j] - mx); sc[kt][j] = pv; den += pv; }
;         sc[9] = (f32x4){0.f, 0.f, 0.f, 0.f};
;         den += __shfl_xor(den, 16); den += __shfl_xor(den, 32);
;         f32x4 oacc[4];
; #pragma unroll
;         for (int et = 0; et < 4; ++et) oacc[et] = (f32x4){0.f, 0.f, 0.f, 0.f};
; #pragma unroll
;         for (int ks = 0; ks < 5; ++ks) {
;             u32x4 pu; pu.x = cvtpk(sc[2 * ks][0], sc[2 * ks][1]); pu.y = cvtpk(sc[2 * ks][2], sc[2 * ks][3]); pu.z = cvtpk(sc[2 * ks + 1][0], sc[2 * ks + 1][1]); pu.w = cvtpk(sc[2 * ks + 1][2], sc[2 * ks + 1][3]);
;             const bf16x8 pf = __builtin_bit_cast(bf16x8, pu);
;             const bf16_t* vrow = Vs + (16 * w4 + 32 * ks + 4 * gq + (ql >> 2)) * ATT_LD + 4 * (ql & 3);
; #pragma unroll
;             for (int et = 0; et < 4; ++et) {
;                 const v4i16_t t0 = lds_tr16(vrow + 16 * et);
;                 v4i16_t t1 = (v4i16_t){0, 0, 0, 0};
;                 if (ks < 4) t1 = lds_tr16(vrow + 16 * ATT_LD + 16 * et);
;                 const bf16x8 vf = __builtin_shufflevector(t0, t1, 0, 1, 2, 3, 4, 5, 6, 7);
;                 oacc[et] = __builtin_amdgcn_mfma_f32_16x16x32_bf16(pf, vf, oacc[et], 0, 0, 0); }
	v_max_f32_e32 v46, v46, v46
	v_max_f32_e32 v13, v13, v46
	v_xor_b32_e32 v46, 32, v183
	v_cmp_lt_i32_e32 vcc, v46, v48
	s_nop 1
	v_cndmask_b32_e32 v46, v183, v46, vcc
	v_lshlrev_b32_e32 v204, 2, v46
	ds_bpermute_b32 v46, v204, v13
	s_waitcnt lgkmcnt(0)
	v_max_f32_e32 v46, v46, v46
	v_max_f32_e32 v46, v13, v46
	v_sub_f32_e32 v13, v194, v46
	v_exp_f32_e32 v13, v13
	v_sub_f32_e32 v49, v195, v46
	v_exp_f32_e32 v49, v49
	v_sub_f32_e32 v194, v196, v46
	v_exp_f32_e32 v194, v194
	v_sub_f32_e32 v195, v197, v46
	v_exp_f32_e32 v195, v195
	v_sub_f32_e32 v14, v14, v46
	v_add_f32_e32 v48, 0, v13
	v_exp_f32_e32 v14, v14
	v_sub_f32_e32 v188, v188, v46
	v_add_f32_e32 v48, v49, v48
	v_exp_f32_e32 v188, v188
	v_sub_f32_e32 v189, v189, v46
	v_add_f32_e32 v48, v194, v48
	v_exp_f32_e32 v189, v189
	v_sub_f32_e32 v190, v190, v46
	v_add_f32_e32 v48, v195, v48
	v_exp_f32_e32 v190, v190
	v_sub_f32_e32 v191, v191, v46
	v_add_f32_e32 v48, v14, v48
	v_exp_f32_e32 v191, v191
	v_sub_f32_e32 v192, v192, v46
	v_add_f32_e32 v48, v188, v48
	v_exp_f32_e32 v192, v192
	v_sub_f32_e32 v193, v193, v46
	v_add_f32_e32 v48, v189, v48
	v_exp_f32_e32 v193, v193
	v_sub_f32_e32 v196, v198, v46
	v_add_f32_e32 v48, v190, v48
	v_exp_f32_e32 v196, v196
	v_sub_f32_e32 v197, v199, v46
	v_add_f32_e32 v48, v191, v48
	v_exp_f32_e32 v197, v197
	v_sub_f32_e32 v198, v200, v46
	v_add_f32_e32 v48, v192, v48
	v_exp_f32_e32 v198, v198
	v_sub_f32_e32 v199, v201, v46
	v_add_f32_e32 v48, v193, v48
	v_exp_f32_e32 v199, v199
	v_sub_f32_e32 v200, v202, v46
	v_add_f32_e32 v48, v196, v48
	v_exp_f32_e32 v200, v200
	v_sub_f32_e32 v186, v186, v46
	v_add_f32_e32 v48, v197, v48
	v_exp_f32_e32 v207, v186
	v_sub_f32_e32 v186, v187, v46
	v_add_f32_e32 v48, v198, v48
	v_exp_f32_e32 v208, v186
	v_sub_f32_e32 v64, v64, v46
	v_add_f32_e32 v48, v199, v48
	v_exp_f32_e32 v64, v64
	v_sub_f32_e32 v65, v65, v46
	v_add_f32_e32 v48, v200, v48
	v_exp_f32_e32 v65, v65
	v_sub_f32_e32 v62, v62, v46
	v_add_f32_e32 v48, v207, v48
	v_exp_f32_e32 v209, v62
	v_sub_f32_e32 v62, v63, v46
	v_add_f32_e32 v48, v208, v48
	v_exp_f32_e32 v210, v62
	v_sub_f32_e32 v60, v60, v46
	v_add_f32_e32 v48, v64, v48
	v_exp_f32_e32 v211, v60
	v_sub_f32_e32 v60, v61, v46
	v_add_f32_e32 v48, v65, v48
	v_exp_f32_e32 v212, v60
	v_sub_f32_e32 v58, v58, v46
	v_add_f32_e32 v48, v209, v48
	v_exp_f32_e32 v213, v58
	v_sub_f32_e32 v58, v59, v46
	v_add_f32_e32 v48, v210, v48
	v_exp_f32_e32 v214, v58
	v_sub_f32_e32 v56, v56, v46
	v_add_f32_e32 v48, v211, v48
	v_exp_f32_e32 v215, v56
	v_sub_f32_e32 v56, v57, v46
	v_add_f32_e32 v48, v212, v48
	v_exp_f32_e32 v216, v56
	v_sub_f32_e32 v54, v54, v46
	v_add_f32_e32 v48, v213, v48
	v_exp_f32_e32 v217, v54
	v_sub_f32_e32 v54, v55, v46
	v_add_f32_e32 v48, v214, v48
	v_exp_f32_e32 v218, v54
	v_sub_f32_e32 v52, v52, v46
	v_add_f32_e32 v48, v215, v48
	v_exp_f32_e32 v219, v52
	v_sub_f32_e32 v52, v53, v46
	v_add_f32_e32 v48, v216, v48
	v_exp_f32_e32 v220, v52
	v_sub_f32_e32 v50, v50, v46
	v_add_f32_e32 v48, v217, v48
	v_exp_f32_e32 v221, v50
	v_add_f32_e32 v48, v218, v48
	v_add_f32_e32 v48, v219, v48
	v_add_f32_e32 v48, v220, v48
	v_add_f32_e32 v201, v221, v48
	v_sub_f32_e32 v48, v51, v46
	v_exp_f32_e32 v222, v48
	v_sub_f32_e32 v47, v47, v46
	v_cvt_pk_bf16_f32 v48, v13, v49
	v_exp_f32_e32 v13, v47
	v_sub_f32_e32 v12, v12, v46
	v_cvt_pk_bf16_f32 v50, v14, v188
	v_exp_f32_e32 v14, v12
	v_add_f32_e32 v12, v222, v201
	v_add_f32_e32 v12, v13, v12
	v_cvt_pk_bf16_f32 v49, v194, v195
	v_add_f32_e32 v12, v14, v12
	ds_bpermute_b32 v47, v203, v12
	v_cvt_pk_bf16_f32 v51, v189, v190
	ds_read_b64_tr_b16 v[54:55], v179 offset:57600
	ds_read_b64_tr_b16 v[52:53], v179 offset:55296
	ds_read_b64_tr_b16 v[56:57], v179 offset:55328
	ds_read_b64_tr_b16 v[60:61], v179 offset:55360
	ds_read_b64_tr_b16 v[186:187], v179 offset:55392
	ds_read_b64_tr_b16 v[58:59], v179 offset:57632
	ds_read_b64_tr_b16 v[62:63], v179 offset:57664
	ds_read_b64_tr_b16 v[188:189], v179 offset:57696
	s_waitcnt lgkmcnt(6)
	v_mfma_f32_16x16x32_bf16 v[52:55], v[48:51], v[52:55], 0
	v_add_f32_e32 v47, v12, v47
	ds_bpermute_b32 v223, v204, v47
	s_waitcnt lgkmcnt(3)
	v_mfma_f32_16x16x32_bf16 v[56:59], v[48:51], v[56:59], 0
	s_waitcnt lgkmcnt(2)
	v_mfma_f32_16x16x32_bf16 v[60:63], v[48:51], v[60:63], 0
	s_waitcnt lgkmcnt(1)
	v_mfma_f32_16x16x32_bf16 v[48:51], v[48:51], v[186:189], 0
	v_cvt_pk_bf16_f32 v186, v191, v192
	v_cvt_pk_bf16_f32 v187, v193, v196
	v_cvt_pk_bf16_f32 v188, v197, v198
	v_cvt_pk_bf16_f32 v189, v199, v200
	ds_read_b64_tr_b16 v[192:193], v179 offset:62208
	ds_read_b64_tr_b16 v[190:191], v179 offset:59904
	ds_read_b64_tr_b16 v[194:195], v179 offset:59936
	ds_read_b64_tr_b16 v[198:199], v179 offset:59968
	ds_read_b64_tr_b16 v[202:203], v179 offset:60000
	ds_read_b64_tr_b16 v[196:197], v179 offset:62240
	ds_read_b64_tr_b16 v[200:201], v179 offset:62272
	ds_read_b64_tr_b16 v[204:205], v179 offset:62304
	s_waitcnt lgkmcnt(6)
	v_mfma_f32_16x16x32_bf16 v[52:55], v[186:189], v[190:193], v[52:55]
	s_waitcnt lgkmcnt(2)
	v_mfma_f32_16x16x32_bf16 v[56:59], v[186:189], v[194:197], v[56:59]
	s_waitcnt lgkmcnt(1)
	v_mfma_f32_16x16x32_bf16 v[60:63], v[186:189], v[198:201], v[60:63]
	s_waitcnt lgkmcnt(0)
	v_mfma_f32_16x16x32_bf16 v[48:51], v[186:189], v[202:205], v[48:51]
	v_cvt_pk_bf16_f32 v186, v207, v208
	v_cvt_pk_bf16_f32 v187, v64, v65
	v_cvt_pk_bf16_f32 v188, v209, v210
	v_cvt_pk_bf16_f32 v189, v211, v212
	ds_read_b64_tr_b16 v[192:193], v180 offset:11520
	ds_read_b64_tr_b16 v[190:191], v179 offset:64512
	ds_read_b64_tr_b16 v[194:195], v179 offset:64544
	ds_read_b64_tr_b16 v[198:199], v179 offset:64576
	ds_read_b64_tr_b16 v[202:203], v179 offset:64608
	ds_read_b64_tr_b16 v[196:197], v180 offset:11552
	ds_read_b64_tr_b16 v[200:201], v180 offset:11584
	ds_read_b64_tr_b16 v[204:205], v180 offset:11616
	s_waitcnt lgkmcnt(6)
; __device__ __forceinline__ unsigned cvtpk(float lo, float hi) { const f32v2_t v = {lo, hi}; const bf16v2_t b = __builtin_convertvector(v, bf16v2_t); return __builtin_bit_cast(unsigned, b); }
; __device__ __forceinline__ bf16_t f2bf(float f) { return (bf16_t)cvtpk(f, 0.f); }
; __device__ __forceinline__ v4i16_t lds_tr16(const bf16_t* p) { return __builtin_amdgcn_ds_read_tr16_b64_v4i16((LAS v4i16_t*)p); }
; __device__ void phase_attn(const Params& p, unsigned char* smem, int wave) {
;     ...
;         for (int ks = 0; ks < 5; ++ks) {
;             u32x4 pu; pu.x = cvtpk(sc[2 * ks][0], sc[2 * ks][1]); pu.y = cvtpk(sc[2 * ks][2], sc[2 * ks][3]); pu.z = cvtpk(sc[2 * ks + 1][0], sc[2 * ks + 1][1]); pu.w = cvtpk(sc[2 * ks + 1][2], sc[2 * ks + 1][3]);
;             const bf16x8 pf = __builtin_bit_cast(bf16x8, pu);
;             const bf16_t* vrow = Vs + (16 * w4 + 32 * ks + 4 * gq + (ql >> 2)) * ATT_LD + 4 * (ql & 3);
; #pragma unroll
;             for (int et = 0; et < 4; ++et) {
;                 const v4i16_t t0 = lds_tr16(vrow + 16 * et);
;                 v4i16_t t1 = (v4i16_t){0, 0, 0, 0};
;                 if (ks < 4) t1 = lds_tr16(vrow + 16 * ATT_LD + 16 * et);
;                 const bf16x8 vf = __builtin_shufflevector(t0, t1, 0, 1, 2, 3, 4, 5, 6, 7);
;                 oacc[et] = __builtin_amdgcn_mfma_f32_16x16x32_bf16(pf, vf, oacc[et], 0, 0, 0); }
;             __builtin_amdgcn_sched_barrier(0);
;         }
; #pragma unroll
;         for (int j = 0; j < 4; ++j) { const float dq = __shfl(den, 4 * gq + j); const float inv = __builtin_amdgcn_rcpf(dq);
;             const int tok = gbase + (i0 + 16 * w4 + 4 * gq + j) * d + res;
; #pragma unroll
;             for (int et = 0; et < 4; ++et) ato[(size_t)tok * 512 + h * 64 + 16 * et + ql] = f2bf(oacc[et][j] * inv); }
;         if (gq == 0) { const int tok = gbase + qi * d + res; lse[((size_t)br * NTOK + tok) * 8 + h] = mx * 0.6931471805599453f + __logf(den); }
	v_mfma_f32_16x16x32_bf16 v[52:55], v[186:189], v[190:193], v[52:55]
	s_waitcnt lgkmcnt(2)
	v_mfma_f32_16x16x32_bf16 v[56:59], v[186:189], v[194:197], v[56:59]
	s_waitcnt lgkmcnt(1)
	v_mfma_f32_16x16x32_bf16 v[60:63], v[186:189], v[198:201], v[60:63]
	s_waitcnt lgkmcnt(0)
	v_mfma_f32_16x16x32_bf16 v[48:51], v[186:189], v[202:205], v[48:51]
	v_cvt_pk_bf16_f32 v186, v213, v214
	v_cvt_pk_bf16_f32 v187, v215, v216
	v_cvt_pk_bf16_f32 v188, v217, v218
	v_cvt_pk_bf16_f32 v189, v219, v220
	ds_read_b64_tr_b16 v[192:193], v180 offset:16128
	ds_read_b64_tr_b16 v[190:191], v180 offset:13824
	ds_read_b64_tr_b16 v[194:195], v180 offset:13856
	ds_read_b64_tr_b16 v[198:199], v180 offset:13888
	ds_read_b64_tr_b16 v[202:203], v180 offset:13920
	ds_read_b64_tr_b16 v[196:197], v180 offset:16160
	ds_read_b64_tr_b16 v[200:201], v180 offset:16192
	ds_read_b64_tr_b16 v[204:205], v180 offset:16224
	s_waitcnt lgkmcnt(6)
	v_mfma_f32_16x16x32_bf16 v[52:55], v[186:189], v[190:193], v[52:55]
	s_waitcnt lgkmcnt(2)
	v_mfma_f32_16x16x32_bf16 v[56:59], v[186:189], v[194:197], v[56:59]
	s_waitcnt lgkmcnt(1)
	v_mfma_f32_16x16x32_bf16 v[60:63], v[186:189], v[198:201], v[60:63]
	s_waitcnt lgkmcnt(0)
	v_mfma_f32_16x16x32_bf16 v[48:51], v[186:189], v[202:205], v[48:51]
	v_cvt_pk_bf16_f32 v12, v221, v222
	v_cvt_pk_bf16_f32 v13, v13, v14
	v_mov_b32_e32 v14, v15
	ds_read_b64_tr_b16 v[186:187], v180 offset:18432
	ds_read_b64_tr_b16 v[190:191], v180 offset:18464
	ds_read_b64_tr_b16 v[194:195], v180 offset:18496
	ds_read_b64_tr_b16 v[198:199], v180 offset:18528
	v_mov_b32_e32 v188, v15
	v_mov_b32_e32 v189, v15
	v_mov_b32_e32 v192, v15
	v_mov_b32_e32 v193, v15
	v_mov_b32_e32 v196, v15
	v_mov_b32_e32 v197, v15
	v_mov_b32_e32 v200, v15
	v_mov_b32_e32 v201, v15
	s_waitcnt lgkmcnt(3)
	v_mfma_f32_16x16x32_bf16 v[52:55], v[12:15], v[186:189], v[52:55]
	s_waitcnt lgkmcnt(2)
	v_mfma_f32_16x16x32_bf16 v[56:59], v[12:15], v[190:193], v[56:59]
	s_waitcnt lgkmcnt(1)
	v_mfma_f32_16x16x32_bf16 v[60:63], v[12:15], v[194:197], v[60:63]
	s_waitcnt lgkmcnt(0)
	v_mfma_f32_16x16x32_bf16 v[48:51], v[12:15], v[198:201], v[48:51]
	v_or_b32_e32 v14, v206, v141
	v_add_f32_e32 v12, v47, v223
	v_lshlrev_b32_e32 v14, 2, v14
	ds_bpermute_b32 v47, v14, v12
	s_add_i32 s62, s62, s61
	s_lshl_b32 s18, s57, 7
	s_add_u32 s18, s59, s18
	v_or_b32_e32 v13, v139, v141
	s_addc_u32 s19, s60, 0
	v_mov_b32_e32 v139, v15
	s_waitcnt lgkmcnt(0)
	v_rcp_f32_e32 v47, v47
	v_lshl_add_u64 v[64:65], s[18:19], 0, v[138:139]
	v_lshlrev_b32_e32 v139, s58, v13
	v_add_u32_e32 v186, s62, v139
	v_ashrrev_i32_e32 v187, 31, v186
	v_lshlrev_b64 v[186:187], 10, v[186:187]
	v_mul_f32_e32 v52, v52, v47
	v_lshl_add_u64 v[186:187], v[64:65], 0, v[186:187]
	v_cvt_pk_bf16_f32 v52, v52, s0
	global_store_short v[186:187], v52, off
	v_mul_f32_e32 v52, v56, v47
	ds_bpermute_b32 v56, v14, v12 offset:4
	v_cvt_pk_bf16_f32 v52, v52, s0
	global_store_short v[186:187], v52, off offset:32
	v_mul_f32_e32 v52, v60, v47
	v_mul_f32_e32 v47, v48, v47
	v_cvt_pk_bf16_f32 v47, v47, s0
	global_store_short v[186:187], v47, off offset:96
	s_waitcnt lgkmcnt(0)
	v_rcp_f32_e32 v47, v56
	v_or_b32_e32 v48, 1, v13
	v_cvt_pk_bf16_f32 v52, v52, s0
	v_lshlrev_b32_e32 v48, s58, v48
	global_store_short v[186:187], v52, off offset:64
	v_add_u32_e32 v186, s62, v48
	v_ashrrev_i32_e32 v187, 31, v186
	v_lshlrev_b64 v[186:187], 10, v[186:187]
	v_mul_f32_e32 v48, v53, v47
	v_lshl_add_u64 v[186:187], v[64:65], 0, v[186:187]
	v_cvt_pk_bf16_f32 v48, v48, s0
	ds_bpermute_b32 v52, v14, v12 offset:8
	global_store_short v[186:187], v48, off
	v_mul_f32_e32 v48, v57, v47
	v_cvt_pk_bf16_f32 v48, v48, s0
	global_store_short v[186:187], v48, off offset:32
	v_mul_f32_e32 v48, v61, v47
	v_mul_f32_e32 v47, v49, v47
	v_cvt_pk_bf16_f32 v48, v48, s0
	v_cvt_pk_bf16_f32 v47, v47, s0
	global_store_short v[186:187], v48, off offset:64
	global_store_short v[186:187], v47, off offset:96
	s_waitcnt lgkmcnt(0)
	v_rcp_f32_e32 v47, v52
	v_or_b32_e32 v48, 2, v13
	v_lshlrev_b32_e32 v48, s58, v48
	v_add_u32_e32 v48, s62, v48
	v_or_b32_e32 v14, 12, v14
	v_ashrrev_i32_e32 v49, 31, v48
	ds_bpermute_b32 v14, v14, v12
	v_lshlrev_b64 v[48:49], 10, v[48:49]
	v_mul_f32_e32 v52, v54, v47
	v_lshl_add_u64 v[48:49], v[64:65], 0, v[48:49]
	v_cvt_pk_bf16_f32 v52, v52, s0
	global_store_short v[48:49], v52, off
	v_mul_f32_e32 v52, v58, v47
	v_cvt_pk_bf16_f32 v52, v52, s0
	global_store_short v[48:49], v52, off offset:32
	v_mul_f32_e32 v52, v62, v47
	v_mul_f32_e32 v47, v50, v47
	s_waitcnt lgkmcnt(0)
	v_rcp_f32_e32 v14, v14
	v_or_b32_e32 v13, 3, v13
	v_cvt_pk_bf16_f32 v52, v52, s0
	v_cvt_pk_bf16_f32 v47, v47, s0
	v_lshlrev_b32_e32 v13, s58, v13
	global_store_short v[48:49], v52, off offset:64
	global_store_short v[48:49], v47, off offset:96
	v_add_u32_e32 v48, s62, v13
	v_ashrrev_i32_e32 v49, 31, v48
	v_lshlrev_b64 v[48:49], 10, v[48:49]
	v_mul_f32_e32 v13, v55, v14
	v_lshl_add_u64 v[48:49], v[64:65], 0, v[48:49]
	v_cvt_pk_bf16_f32 v13, v13, s0
	global_store_short v[48:49], v13, off
	v_mul_f32_e32 v13, v59, v14
	v_cvt_pk_bf16_f32 v13, v13, s0
	global_store_short v[48:49], v13, off offset:32
	v_mul_f32_e32 v13, v63, v14
	v_cvt_pk_bf16_f32 v13, v13, s0
	global_store_short v[48:49], v13, off offset:64
	v_mul_f32_e32 v13, v51, v14
	v_cvt_pk_bf16_f32 v13, v13, s0
	global_store_short v[48:49], v13, off offset:96
	s_and_saveexec_b64 s[20:21], s[0:1]
	s_cbranch_execz .LBB0_719
	v_cmp_gt_f32_e32 vcc, s53, v12
	s_nop 1
	v_cndmask_b32_e64 v13, 0, 32, vcc
	v_ldexp_f32 v12, v12, v13
	v_log_f32_e32 v13, v12
	v_lshlrev_b32_e32 v12, s58, v45
	v_add_u32_e32 v12, s62, v12
	v_mul_f32_e32 v14, 0x3f317217, v13
	v_fma_f32 v14, v13, s54, -v14
	v_fmac_f32_e32 v14, 0x3377d1cf, v13
	v_fmac_f32_e32 v14, 0x3f317217, v13
	v_cmp_lt_f32_e64 s[18:19], |v13|, s55
	s_nop 1
	v_cndmask_b32_e64 v13, v13, v14, s[18:19]
	v_cndmask_b32_e32 v14, 0, v184, vcc
	v_sub_f32_e32 v14, v13, v14
	v_ashrrev_i32_e32 v13, 31, v12
	v_mad_i64_i32 v[12:13], s[18:19], s42, v185, v[12:13]
	v_lshlrev_b64 v[12:13], 5, v[12:13]
	v_lshl_add_u64 v[12:13], s[40:41], 0, v[12:13]
	s_lshl_b32 s42, s57, 2
	v_fmac_f32_e32 v14, 0x3f317218, v46
	v_lshl_add_u64 v[12:13], v[12:13], 0, s[42:43]
	global_store_dword v[12:13], v14, off
	s_branch .LBB0_719
